# diff fast loop: row sums via four 16x16x32 bf16 MFMAs with a 0/1 selection-matrix A operand (complete per-query sums in every lane, no cross-half fold) instead of eight 4x4x4 MFMAs
# speedup vs baseline: 1.0157x; 1.0157x over previous
.LBB0_457:
	v_readlane_b32 s2, v254, 36
	s_add_i32 s7, s6, s2
	s_cmpk_gt_i32 s7, 0x7ff
	s_mov_b64 s[4:5], -1
	s_cbranch_scc1 .LBB0_456
	v_readlane_b32 s2, v253, 51
	v_readlane_b32 s4, v253, 49
	s_add_i32 s8, s6, s2
	s_ashr_i32 s9, s7, 5
	v_readlane_b32 s5, v253, 50
	s_and_b64 s[4:5], s[4:5], exec
	s_cselect_b32 s4, s85, s7
	s_cselect_b32 s5, s8, s9
	s_lshl_b32 s4, s4, 7
	s_and_b32 s16, s4, 0xf80
	s_lshl_b32 s4, s5, 7
	s_ashr_i32 s7, s5, 3
	s_and_b32 s8, s4, 0x380
	s_lshl_b32 s9, s7, 12
	s_lshl_b32 s10, s7, 8
	s_lshr_b32 s7, s8, 6
	s_add_i32 s10, s10, 0x8000
	s_mul_i32 s11, s7, 0x8800
	s_ashr_i32 s17, s9, 31
	v_mbcnt_lo_u32_b32 v0, -1, 0
	v_mbcnt_hi_u32_b32 v0, -1, v0
	s_add_u32 s4, s11, s9
	v_add_u32_e32 v187, s69, v0
	s_addc_u32 s5, 0, s17
	v_and_b32_e32 v0, 7, v187
	v_bfe_u32 v188, v187, 4, 2
	v_bitop3_b32 v0, v188, v0, s83 bitop3:0x36
	s_lshl_b64 s[4:5], s[4:5], 7
	v_and_or_b32 v0, v187, 56, v0
	s_add_u32 s12, s95, s4
	v_lshl_or_b32 v212, v0, 4, s46
	s_addc_u32 s13, s3, s5
	s_mov_b32 s19, m0
	s_mov_b32 m0, s23
	s_nop 0
	global_load_lds_dwordx4 v212, s[12:13]
	s_mov_b32 m0, s19
	s_add_i32 s12, s11, 0x8800
	s_add_u32 s28, s12, s9
	s_addc_u32 s29, 0, s17
	s_lshl_b64 s[28:29], s[28:29], 7
	v_bfe_u32 v5, v187, 5, 1
	v_lshlrev_b32_e32 v190, 4, v187
	s_add_u32 s28, s95, s28
	v_or_b32_e32 v2, s25, v5
	v_and_b32_e32 v3, 0x1c0, v190
	v_lshlrev_b32_e32 v189, 3, v187
	s_addc_u32 s29, s3, s29
	s_add_i32 s13, s23, 0x2000
	v_lshl_or_b32 v2, v2, 9, v3
	v_and_b32_e32 v6, 24, v189
	v_readlane_b32 s2, v253, 62
	s_add_u32 s4, s14, s4
	s_mov_b32 s17, m0
	s_mov_b32 m0, s13
	s_nop 0
	global_load_lds_dwordx4 v212, s[28:29]
	s_mov_b32 m0, s17
	s_addc_u32 s5, s15, s5
	v_or3_b32 v2, v2, s2, v6
	v_readlane_b32 s2, v253, 63
	s_add_i32 s13, s23, 0x4000
	v_and_b32_e32 v191, 31, v187
	v_add_lshl_u32 v222, v2, s2, 1
	s_mov_b32 s17, m0
	s_mov_b32 m0, s13
	s_nop 0
	global_load_lds_dwordx4 v222, s[4:5]
	s_mov_b32 m0, s17
	v_readlane_b32 s2, v254, 26
	s_add_i32 s13, s23, 0x6000
	v_lshlrev_b32_e32 v0, 4, v5
	v_add_lshl_u32 v223, v2, s2, 1
	s_mov_b32 s17, m0
	s_mov_b32 m0, s13
	s_nop 0
	global_load_lds_dwordx4 v223, s[4:5]
	s_mov_b32 m0, s17
	s_or_b32 s13, s9, 64
	s_ashr_i32 s17, s13, 31
	s_add_u32 s4, s11, s13
	s_addc_u32 s5, 0, s17
	s_lshl_b64 s[4:5], s[4:5], 7
	s_add_u32 s28, s95, s4
	s_addc_u32 s29, s3, s5
	s_add_i32 s19, s23, 0x8000
	s_mov_b32 s20, m0
	s_mov_b32 m0, s19
	s_nop 0
	global_load_lds_dwordx4 v212, s[28:29]
	s_mov_b32 m0, s20
	s_add_u32 s28, s12, s13
	s_addc_u32 s29, 0, s17
	s_lshl_b64 s[28:29], s[28:29], 7
	s_add_u32 s28, s95, s28
	s_addc_u32 s29, s3, s29
	s_add_i32 s13, s23, 0xa000
	s_mov_b32 s17, m0
	s_mov_b32 m0, s13
	s_nop 0
	global_load_lds_dwordx4 v212, s[28:29]
	s_mov_b32 m0, s17
	s_add_u32 s4, s14, s4
	s_addc_u32 s5, s15, s5
	s_add_i32 s13, s23, 0xc000
	s_mov_b32 s17, m0
	s_mov_b32 m0, s13
	s_nop 0
	global_load_lds_dwordx4 v222, s[4:5]
	s_mov_b32 m0, s17
	v_readlane_b32 s2, v254, 33
	s_add_i32 s13, s23, 0xe000
	s_mov_b32 s17, m0
	s_mov_b32 m0, s13
	s_nop 0
	global_load_lds_dwordx4 v223, s[4:5]
	s_mov_b32 m0, s17
	s_add_i32 s4, s7, s2
	v_readlane_b32 s2, v253, 53
	s_or_b32 s5, s16, s2
	s_or_b32 s7, s5, s9
	v_or_b32_e32 v2, s7, v191
	v_ashrrev_i32_e32 v3, 31, v2
	v_mad_u64_u32 v[2:3], s[4:5], s4, v217, v[2:3]
	v_lshlrev_b64 v[2:3], 7, v[2:3]
	v_lshl_add_u64 v[2:3], s[58:59], 0, v[2:3]
	v_lshl_add_u64 v[2:3], v[2:3], 0, v[0:1]
	global_load_dwordx4 v[144:147], v[2:3], off offset:96
	global_load_dwordx4 v[148:151], v[2:3], off offset:64
	global_load_dwordx4 v[152:155], v[2:3], off offset:32
	global_load_dwordx4 v[156:159], v[2:3], off
	v_lshrrev_b32_e32 v0, 1, v187
	v_lshrrev_b32_e32 v7, 2, v187
	v_lshlrev_b32_e32 v193, 2, v5
	v_lshlrev_b32_e32 v8, 1, v187
	v_bfe_u32 v9, v187, 1, 3
	v_bitop3_b32 v0, v5, v0, 7 bitop3:0x78
	v_and_or_b32 v7, v7, 3, v193
	v_lshlrev_b32_e32 v192, 3, v5
	v_and_b32_e32 v8, 32, v8
	v_bitop3_b32 v10, v5, v9, 2 bitop3:0x36
	v_bitop3_b32 v11, v5, v9, 4 bitop3:0x36
	v_bitop3_b32 v5, v5, v9, 6 bitop3:0x36
	v_lshlrev_b32_e32 v228, 4, v0
	v_lshlrev_b32_e32 v0, 6, v7
	v_mov_b32_e32 v14, v1
	v_mov_b32_e32 v15, v1
	v_mov_b32_e32 v2, v1
	v_mov_b32_e32 v3, v1
	v_mov_b32_e32 v4, v1
	v_lshlrev_b32_e32 v226, 4, v10
	v_lshlrev_b32_e32 v225, 4, v11
	v_lshlrev_b32_e32 v224, 4, v5
	v_or3_b32 v210, v0, v8, v6
	v_mov_b32_e32 v0, v1
	v_mov_b32_e32 v5, v1
	v_mov_b32_e32 v6, v1
	v_mov_b32_e32 v7, v1
	v_mov_b32_e32 v8, v1
	v_mov_b32_e32 v9, v1
	v_mov_b32_e32 v10, v1
	v_mov_b32_e32 v11, v1
	v_mov_b32_e32 v12, v1
	v_mov_b32_e32 v13, v1
	v_mov_b64_e32 v[78:79], v[14:15]
	v_mov_b64_e32 v[62:63], v[14:15]
	v_mov_b64_e32 v[46:47], v[14:15]
	v_mov_b64_e32 v[30:31], v[14:15]
	v_mov_b64_e32 v[94:95], v[14:15]
	s_mov_b32 s13, 2
	s_mov_b32 s19, 0
	v_and_b32_e32 v194, 63, v187
	v_lshl_add_u32 v227, v191, 7, s21
	v_add_u32_e32 v195, 0, v210
	s_mov_b64 s[4:5], -1
	v_mov_b32_e32 v209, 0
	v_mov_b32_e32 v140, 0
	v_mov_b32_e32 v141, 0
	v_mov_b32_e32 v142, 0
	v_mov_b32_e32 v143, 0
	v_mov_b32_e32 v136, 0
	v_mov_b32_e32 v137, 0
	v_mov_b32_e32 v138, 0
	v_mov_b32_e32 v139, 0
	v_mov_b32_e32 v132, 0
	v_mov_b32_e32 v133, 0
	v_mov_b32_e32 v134, 0
	v_mov_b32_e32 v135, 0
	v_mov_b32_e32 v128, 0
	v_mov_b32_e32 v129, 0
	v_mov_b32_e32 v130, 0
	v_mov_b32_e32 v131, 0
	v_mov_b64_e32 v[76:77], v[12:13]
	v_mov_b64_e32 v[74:75], v[10:11]
	v_mov_b64_e32 v[72:73], v[8:9]
	v_mov_b64_e32 v[70:71], v[6:7]
	v_mov_b64_e32 v[68:69], v[4:5]
	v_mov_b64_e32 v[66:67], v[2:3]
	v_mov_b64_e32 v[64:65], v[0:1]
	v_mov_b64_e32 v[60:61], v[12:13]
	v_mov_b64_e32 v[58:59], v[10:11]
	v_mov_b64_e32 v[56:57], v[8:9]
	v_mov_b64_e32 v[54:55], v[6:7]
	v_mov_b64_e32 v[52:53], v[4:5]
	v_mov_b64_e32 v[50:51], v[2:3]
	v_mov_b64_e32 v[48:49], v[0:1]
	v_mov_b64_e32 v[44:45], v[12:13]
	v_mov_b64_e32 v[42:43], v[10:11]
	v_mov_b64_e32 v[40:41], v[8:9]
	v_mov_b64_e32 v[38:39], v[6:7]
	v_mov_b64_e32 v[36:37], v[4:5]
	v_mov_b64_e32 v[34:35], v[2:3]
	v_mov_b64_e32 v[32:33], v[0:1]
	v_mov_b64_e32 v[28:29], v[12:13]
	v_mov_b64_e32 v[26:27], v[10:11]
	v_mov_b64_e32 v[24:25], v[8:9]
	v_mov_b64_e32 v[22:23], v[6:7]
	v_mov_b64_e32 v[20:21], v[4:5]
	v_mov_b64_e32 v[18:19], v[2:3]
	v_mov_b64_e32 v[16:17], v[0:1]
	v_mov_b64_e32 v[92:93], v[12:13]
	v_mov_b64_e32 v[90:91], v[10:11]
	v_mov_b64_e32 v[88:89], v[8:9]
	v_mov_b64_e32 v[86:87], v[6:7]
	v_mov_b64_e32 v[84:85], v[4:5]
	v_mov_b64_e32 v[82:83], v[2:3]
	v_mov_b64_e32 v[80:81], v[0:1]
	s_mov_b32 s28, 0
	s_waitcnt vmcnt(0)
	v_mov_b32_e32 v218, s60
	v_mov_b32_e32 v219, s60
	v_mov_b32_e32 v220, s60
	v_mov_b32_e32 v221, s60
	s_add_i32 s20, s19, 0x10000
	s_and_b32 s20, s20, 0x18000
	s_add_i32 s20, s20, s23
	s_add_i32 s62, s13, -2
	s_cmpk_gt_u32 s62, 0x41
	s_cselect_b32 s61, 1, 0
	s_cmp_lt_u32 s62, 62
	s_cselect_b32 s16, 0, 0xffffffc0
	s_cselect_b32 s17, s9, s10
	s_add_i32 s16, s16, s13
	s_lshl_b32 s16, s16, 6
	s_add_i32 s62, s16, s17
	s_ashr_i32 s63, s62, 31
	s_add_u32 s30, s62, s11
	s_addc_u32 s31, s63, 0
	s_lshl_b64 s[30:31], s[30:31], 7
	s_add_u32 s34, s95, s30
	s_addc_u32 s35, s3, s31
	s_add_u32 s16, s62, s12
	s_addc_u32 s17, s63, 0
	s_lshl_b64 s[16:17], s[16:17], 7
	s_add_u32 s16, s95, s16
	s_addc_u32 s17, s3, s17
	s_add_u32 s30, s14, s30
	s_addc_u32 s31, s15, s31
	v_mbcnt_lo_u32_b32 v94, -1, 0
	v_mbcnt_hi_u32_b32 v94, -1, v94
	v_lshrrev_b32_e32 v92, 4, v94
	v_lshrrev_b32_e32 v93, 2, v94
	v_xor_b32_e32 v92, v92, v93
	v_and_b32_e32 v92, 1, v92
	v_mov_b32_e32 v93, s60
	v_cmp_eq_u32_e64 s[62:63], 0, v92
	s_nop 1
	v_cndmask_b32_e64 v92, 0, v93, s[62:63]
	v_mov_b32_e32 v93, v92
	v_mov_b32_e32 v94, v92
	v_mov_b32_e32 v95, v92
	s_nop 1
	s_branch .Lf_460

.Lf_459:
	v_mov_b32_e32 v180, v128
	v_mov_b32_e32 v181, v129
	v_mov_b32_e32 v182, v130
	v_mov_b32_e32 v183, v131
	v_mfma_f32_32x32x16_bf16 v[64:79], v[176:179], v[140:143], v[64:79]
	ds_read_b64_tr_b16 v[128:129], v0 offset:24576
	ds_read_b64_tr_b16 v[130:131], v0 offset:25088
	v_exp_f32_e32 v14, v112
	v_mfma_f32_32x32x16_bf16 v[64:79], v[172:175], v[136:139], v[64:79]
	ds_read_b64_tr_b16 v[172:173], v0 offset:25600
	ds_read_b64_tr_b16 v[174:175], v0 offset:26112
	v_exp_f32_e32 v15, v96
	v_mfma_f32_32x32x16_bf16 v[64:79], v[168:171], v[132:135], v[64:79]
	ds_read_b64_tr_b16 v[168:169], v0 offset:26624
	ds_read_b64_tr_b16 v[170:171], v0 offset:27136
	v_exp_f32_e32 v96, v113
	v_mfma_f32_32x32x16_bf16 v[64:79], v[164:167], v[180:183], v[64:79]
	ds_read_b64_tr_b16 v[164:165], v0 offset:27648
	ds_read_b64_tr_b16 v[166:167], v0 offset:28160
	v_exp_f32_e32 v97, v97
	v_mfma_f32_32x32x16_bf16 v[48:63], v[160:163], v[140:143], v[48:63]
	ds_read_b64_tr_b16 v[160:161], v0 offset:28672
	ds_read_b64_tr_b16 v[162:163], v0 offset:29184
	v_exp_f32_e32 v112, v114
	v_mfma_f32_32x32x16_bf16 v[48:63], v[10:13], v[136:139], v[48:63]
	ds_read_b64_tr_b16 v[10:11], v0 offset:29696
	ds_read_b64_tr_b16 v[12:13], v0 offset:30208
	v_exp_f32_e32 v98, v98
	v_mfma_f32_32x32x16_bf16 v[48:63], v[6:9], v[132:135], v[48:63]
	ds_read_b64_tr_b16 v[6:7], v0 offset:30720
	ds_read_b64_tr_b16 v[8:9], v0 offset:31232
	v_exp_f32_e32 v113, v115
	v_mfma_f32_32x32x16_bf16 v[48:63], v[2:5], v[180:183], v[48:63]
	ds_read_b64_tr_b16 v[2:3], v0 offset:31744
	ds_read_b64_tr_b16 v[4:5], v0 offset:32256
	v_exp_f32_e32 v0, v99
	s_waitcnt lgkmcnt(14)
	v_mfma_f32_32x32x16_bf16 v[32:47], v[128:131], v[140:143], v[32:47]
	v_exp_f32_e32 v99, v116
	v_exp_f32_e32 v100, v100
	v_exp_f32_e32 v114, v117
	s_waitcnt lgkmcnt(12)
	v_mfma_f32_32x32x16_bf16 v[32:47], v[172:175], v[136:139], v[32:47]
	v_exp_f32_e32 v101, v101
	v_exp_f32_e32 v115, v118
	v_exp_f32_e32 v102, v102
	s_waitcnt lgkmcnt(10)
	v_mfma_f32_32x32x16_bf16 v[32:47], v[168:171], v[132:135], v[32:47]
	v_exp_f32_e32 v116, v119
	v_exp_f32_e32 v103, v103
	v_exp_f32_e32 v117, v120
	s_waitcnt lgkmcnt(8)
	v_mfma_f32_32x32x16_bf16 v[32:47], v[164:167], v[180:183], v[32:47]
	v_exp_f32_e32 v104, v104
	v_exp_f32_e32 v118, v121
	v_exp_f32_e32 v105, v105
	s_waitcnt lgkmcnt(6)
	v_mfma_f32_32x32x16_bf16 v[16:31], v[160:163], v[140:143], v[16:31]
	v_exp_f32_e32 v119, v122
	v_exp_f32_e32 v106, v106
	v_exp_f32_e32 v120, v123
	s_waitcnt lgkmcnt(4)
	v_mfma_f32_32x32x16_bf16 v[16:31], v[10:13], v[136:139], v[16:31]
	v_exp_f32_e32 v10, v107
	v_exp_f32_e32 v11, v124
	v_exp_f32_e32 v12, v108
	s_waitcnt lgkmcnt(2)
	v_mfma_f32_32x32x16_bf16 v[16:31], v[6:9], v[132:135], v[16:31]
	v_exp_f32_e32 v6, v125
	v_exp_f32_e32 v7, v109
	v_exp_f32_e32 v8, v126
	s_waitcnt lgkmcnt(0)
	v_mfma_f32_32x32x16_bf16 v[16:31], v[2:5], v[180:183], v[16:31]
	v_exp_f32_e32 v107, v110
	s_nop 0
	v_mfma_f32_16x16x32_bf16 v[84:87], v[92:95], v[140:143], v[84:87]
	v_exp_f32_e32 v108, v127
	v_exp_f32_e32 v109, v111
	v_cvt_pk_bf16_f32 v140, v14, v96
	v_cvt_pk_bf16_f32 v143, v115, v116
	v_mfma_f32_16x16x32_bf16 v[84:87], v[92:95], v[136:139], v[84:87]
	v_cvt_pk_bf16_f32 v128, v104, v105
	v_cvt_pk_bf16_f32 v141, v112, v113
	v_cvt_pk_bf16_f32 v136, v117, v118
	v_mfma_f32_16x16x32_bf16 v[84:87], v[92:95], v[132:135], v[84:87]
	v_cvt_pk_bf16_f32 v137, v119, v120
	v_cvt_pk_bf16_f32 v129, v106, v10
	v_cvt_pk_bf16_f32 v132, v15, v97
	v_cvt_pk_bf16_f32 v130, v12, v7
	v_cvt_pk_bf16_f32 v138, v11, v6
	v_cvt_pk_bf16_f32 v133, v98, v0
	v_cvt_pk_bf16_f32 v142, v99, v114
	v_cvt_pk_bf16_f32 v134, v100, v101
	v_cvt_pk_bf16_f32 v135, v102, v103
	v_cvt_pk_bf16_f32 v139, v8, v108
	v_cvt_pk_bf16_f32 v131, v107, v109
	v_mfma_f32_16x16x32_bf16 v[84:87], v[92:95], v[180:183], v[84:87]
	s_add_i32 s28, s28, 1
	s_add_i32 s13, s13, 1
	s_add_i32 s19, s19, 0x8000
	s_cmpk_eq_i32 s13, 0x45
	s_cbranch_scc1 .Lf_fold464

.Lf_foldrare:
	s_nop 7
	v_mov_b32_e32 v80, v84
	s_nop 0
	v_mov_b32_e32 v81, v80
	v_mov_b32_e32 v82, v80
	v_mov_b32_e32 v83, v80
	v_mov_b32_e32 v84, v80
	v_mov_b32_e32 v85, v80
	v_mov_b32_e32 v86, v80
	v_mov_b32_e32 v87, v80
	v_mov_b32_e32 v88, v80
	v_mov_b32_e32 v89, v80
	v_mov_b32_e32 v90, v80
	v_mov_b32_e32 v91, v80
	v_mov_b32_e32 v92, v80
	v_mov_b32_e32 v93, v80
	v_mov_b32_e32 v94, v80
	v_mov_b32_e32 v95, v80
	s_nop 1
	s_branch .Lf_to463
.Lf_fold464:
	s_nop 7
	v_mov_b32_e32 v80, v84
	s_nop 0
	v_mov_b32_e32 v81, v80
	v_mov_b32_e32 v82, v80
	v_mov_b32_e32 v83, v80
	v_mov_b32_e32 v84, v80
	v_mov_b32_e32 v85, v80
	v_mov_b32_e32 v86, v80
	v_mov_b32_e32 v87, v80
	v_mov_b32_e32 v88, v80
	v_mov_b32_e32 v89, v80
	v_mov_b32_e32 v90, v80
	v_mov_b32_e32 v91, v80
	v_mov_b32_e32 v92, v80
	v_mov_b32_e32 v93, v80
	v_mov_b32_e32 v94, v80
	v_mov_b32_e32 v95, v80
	s_nop 1
	s_branch .LBB0_464
	.p2align 6
